# in-proj row-scale prefetch hoisted to the unit head (v156/v158 rematerialized from tid in the epilogue to free two VGPRs across the K-loop), on top of v060
# speedup vs baseline: 1.0216x; 1.0058x over previous
;   __device__ __forceinline__ bool next(int i,AttnUnit&u)const{ if(i>=2)return false; const int s=vcu&15; u.bh=vcu>>4; u.qb=(i==0)?31-s:s; return true; }
; #define RS ((float*)(WSP() + WS_RS))
;     __host__ __device__ bool next(int i, Unit& u) const {
;         const long L = (long)i * G + c; if (L >= nwg) return false;
;         int wgid = (int)L; { const int q = nwg / NXCD, r = nwg % NXCD, xcd = wgid % NXCD, off = wgid / NXCD; wgid = (xcd < r ? xcd * (q + 1) : r * (q + 1) + (xcd - r) * q) + off; }
;         const int nig = WGM * nN, gid = wgid / nig, fm = gid * WGM, gsz = (nM - fm) < WGM ? (nM - fm) : WGM;
;         u.pm = fm + ((wgid % nig) % gsz); u.pn = (wgid % nig) / gsz; return true;
;     __device__ __forceinline__ void operator()(const f32x4 (&acc)[2][2][4][2], const Unit& u, int wr, int wc, int fr, int fq) const {
;     ...
;             for (int m = 0; m < 4; ++m) { const size_t off = (size_t)(row0 + ai * HALF + m * 16) * ldc + col0; const float rs = (MODE != 0) ? RS[row0 + ai * HALF + m * 16] : 1.f;
.LBB0_183:
	v_lshrrev_b32_e32 v156, 2, v200
	v_and_b32_e32 v158, 63, v200
	v_and_or_b32 v156, v156, 64, v158
	v_lshl_add_u32 v156, s24, 8, v156
	v_lshlrev_b32_e32 v156, 2, v156
	global_load_dword v195, v156, s[12:13]
	global_load_dword v158, v156, s[12:13] offset:512
	s_add_i32 s77, s77, 1
	s_mul_i32 s6, s77, s80
	s_mul_hi_u32 s7, s77, s35
	s_add_i32 s7, s7, s6
	s_mul_i32 s6, s77, s35
	s_add_u32 s20, s6, s2
	s_addc_u32 s21, s7, s48
	s_waitcnt lgkmcnt(0)
	v_mov_b64_e32 v[2:3], 0x480
	v_cmp_lt_i64_e64 s[6:7], s[20:21], v[2:3]
	v_mov_b64_e32 v[2:3], 0x47f
	v_cmp_gt_i64_e32 vcc, s[20:21], v[2:3]
	s_cbranch_vccnz .LBB0_185
	s_ashr_i32 s16, s20, 31
	s_lshr_b32 s16, s16, 29
	s_add_i32 s16, s20, s16
	s_ashr_i32 s17, s16, 3
	s_and_b32 s16, s16, -8
	s_sub_i32 s16, s20, s16
	s_cmp_lt_i32 s16, 0
	s_movk_i32 s18, 0x91
	s_cselect_b32 s18, s18, 0x90
	s_mul_i32 s16, s16, s18
	s_add_i32 s16, s16, s17
	s_mul_hi_i32 s17, s16, 0x38e38e39
	s_lshr_b32 s18, s17, 31
	s_ashr_i32 s17, s17, 3
	s_add_i32 s17, s17, s18
	s_lshl_b32 s18, s17, 2
	s_sub_i32 s19, 0x80, s18
	s_min_i32 s19, s19, 4
	s_abs_i32 s20, s19
	v_cvt_f32_u32_e32 v2, s20
	s_sub_i32 s22, 0, s20
	s_mul_i32 s17, s17, 36
	s_sub_i32 s17, s16, s17
	v_rcp_iflag_f32_e32 v2, v2
	s_abs_i32 s16, s17
	s_xor_b32 s21, s17, s19
	s_ashr_i32 s21, s21, 31
	v_mul_f32_e32 v2, 0x4f7ffffe, v2
	v_cvt_u32_f32_e32 v2, v2
	s_nop 0
	v_readfirstlane_b32 s23, v2
	s_mul_i32 s22, s22, s23
	s_mul_hi_u32 s22, s23, s22
	s_add_i32 s23, s23, s22
	s_mul_hi_u32 s22, s16, s23
	s_mul_i32 s23, s22, s20
	s_sub_i32 s16, s16, s23
	s_add_i32 s30, s22, 1
	s_sub_i32 s23, s16, s20
	s_cmp_ge_u32 s16, s20
	s_cselect_b32 s22, s30, s22
	s_cselect_b32 s16, s23, s16
	s_add_i32 s23, s22, 1
	s_cmp_ge_u32 s16, s20
	s_cselect_b32 s16, s23, s22
	s_xor_b32 s16, s16, s21
	s_sub_i32 s16, s16, s21
	s_mul_i32 s19, s16, s19
	s_sub_i32 s17, s17, s19
	s_add_i32 s18, s18, s17

; __device__ __forceinline__ unsigned cvt_pk_bf16(float lo, float hi) { unsigned r; asm volatile("v_cvt_pk_bf16_f32 %0, %1, %2" : "=v"(r) : "v"(lo), "v"(hi)); return r; }
; __device__ __forceinline__ float bf_lo(unsigned w) { return __uint_as_float(w << 16); }
; __device__ __forceinline__ float bf_hi(unsigned w) { return __uint_as_float(w & 0xffff0000u); }
; __device__ __forceinline__ float sigmoid_f(float x) { return __builtin_amdgcn_rcpf(1.0f + __builtin_amdgcn_exp2f(-1.4426950408889634f * x)); }
; #define RS ((float*)(WSP() + WS_RS))
;     __device__ __forceinline__ void operator()(const f32x4 (&acc)[2][2][4][2], const Unit& u, int wr, int wc, int fr, int fq) const {
;         const int row0 = u.pm * BM + wr * 64 + fr; const int col0 = u.pn * BM + wc * 32 + 8 * fq;
;         const float sc = (MODE == 2 && u.pn == qtile) ? qscale : 1.f;
; #pragma unroll
;         for (int ai = 0; ai < 2; ++ai)
; #pragma unroll
;             for (int m = 0; m < 4; ++m) { const size_t off = (size_t)(row0 + ai * HALF + m * 16) * ldc + col0; const float rs = (MODE != 0) ? RS[row0 + ai * HALF + m * 16] : 1.f;
; #pragma unroll
;                 for (int bj = 0; bj < 2; ++bj) { f32x4 v0 = acc[ai][bj][m][0], v1 = acc[ai][bj][m][1];
;                     if (MODE != 0) { v0 = v0 * rs; v1 = v1 * rs; }
;                     if (MODE == 1) {
; #pragma unroll
;                         for (int e = 0; e < 4; ++e) { const float a = fmaxf(v0[e], 0.f), b = fmaxf(v1[e], 0.f); v0[e] = a * a; v1[e] = b * b; } }
;                     if (MODE == 2) { v0 = v0 * sc; v1 = v1 * sc; }
;                     if (MODE == 3) { const u32x4 pw = *(const u32x4*)(P + off + bj * HALF);
;                         v0[0] = bf_lo(pw.x) * sigmoid_f(v0[0]); v0[1] = bf_hi(pw.x) * sigmoid_f(v0[1]); v0[2] = bf_lo(pw.y) * sigmoid_f(v0[2]); v0[3] = bf_hi(pw.y) * sigmoid_f(v0[3]);
;                         v1[0] = bf_lo(pw.z) * sigmoid_f(v1[0]); v1[1] = bf_hi(pw.z) * sigmoid_f(v1[1]); v1[2] = bf_lo(pw.w) * sigmoid_f(v1[2]); v1[3] = bf_hi(pw.w) * sigmoid_f(v1[3]); }
;                     u32x4 w; w.x = cvt_pk_bf16(v0[0], v0[1]); w.y = cvt_pk_bf16(v0[2], v0[3]); w.z = cvt_pk_bf16(v1[0], v1[1]); w.w = cvt_pk_bf16(v1[2], v1[3]);
;                     *(u32x4*)(O + off + bj * HALF) = w; } }
.LBB0_189:
	v_and_b32_e32 v233, 15, v200
	v_lshrrev_b32_e32 v244, 2, v200
	v_and_or_b32 v244, v244, 64, v233
	v_lshrrev_b32_e32 v245, 1, v200
	v_and_b32_e32 v245, 0x78, v245
	v_lshlrev_b32_e32 v234, 2, v233
	v_add_u32_e32 v235, 64, v234
	v_add_u32_e32 v236, 0x80, v234
	v_add_u32_e32 v237, 0xc0, v234
	ds_bpermute_b32 v238, v234, v158
	ds_bpermute_b32 v239, v235, v158
	ds_bpermute_b32 v240, v236, v158
	ds_bpermute_b32 v241, v237, v158
	ds_bpermute_b32 v234, v234, v195
	ds_bpermute_b32 v235, v235, v195
	ds_bpermute_b32 v236, v236, v195
	ds_bpermute_b32 v237, v237, v195
	s_waitcnt lgkmcnt(0)
	v_lshl_add_u32 v150, s24, 8, v244
	v_ashrrev_i32_e32 v151, 31, v150
	v_lshl_add_u64 v[142:143], v[150:151], 2, s[12:13]
	s_nop 1
	v_mov_b32_e32 v160, v234
	s_cmp_eq_u32 s25, 2
	s_cselect_b64 vcc, -1, 0
	v_mov_b32_e32 v140, 0x3e38aa3b
	v_cndmask_b32_e32 v140, 1.0, v140, vcc
	v_lshl_or_b32 v148, s25, 8, v245
	v_ashrrev_i32_e32 v149, 31, v148
	v_add_u32_e32 v151, 0x80, v150
	s_and_b32 s17, s25, -2
	s_cmp_lg_u32 s17, 2
	v_pk_mul_f32 v[144:145], v[126:127], v[160:161] op_sel_hi:[1,0]
	v_pk_mul_f32 v[146:147], v[128:129], v[160:161] op_sel_hi:[1,0]
	v_pk_mul_f32 v[152:153], v[122:123], v[160:161] op_sel_hi:[1,0]
	v_pk_mul_f32 v[154:155], v[124:125], v[160:161] op_sel_hi:[1,0]
	v_pk_mul_f32 v[146:147], v[140:141], v[146:147] op_sel_hi:[0,1]
	v_pk_mul_f32 v[144:145], v[140:141], v[144:145] op_sel_hi:[0,1]
	v_pk_mul_f32 v[152:153], v[140:141], v[152:153] op_sel_hi:[0,1]
	v_pk_mul_f32 v[154:155], v[140:141], v[154:155] op_sel_hi:[0,1]
	v_cvt_pk_bf16_f32 v144, v144, v145
	v_cvt_pk_bf16_f32 v145, v146, v147
	v_cvt_pk_bf16_f32 v146, v152, v153
	v_mov_b64_e32 v[152:153], s[10:11]
	v_cvt_pk_bf16_f32 v147, v154, v155
	v_mad_i64_i32 v[162:163], s[26:27], v150, s97, v[152:153]
	v_lshlrev_b64 v[154:155], 1, v[148:149]
	v_lshl_add_u64 v[148:149], v[162:163], 0, v[154:155]
	global_store_dwordx4 v[148:149], v[144:147], off
	v_pk_mul_f32 v[162:163], v[82:83], v[160:161] op_sel_hi:[1,0]
	s_nop 0
	v_pk_mul_f32 v[144:145], v[90:91], v[160:161] op_sel_hi:[1,0]
	v_pk_mul_f32 v[146:147], v[92:93], v[160:161] op_sel_hi:[1,0]
	v_pk_mul_f32 v[160:161], v[84:85], v[160:161] op_sel_hi:[1,0]
	v_pk_mul_f32 v[146:147], v[140:141], v[146:147] op_sel_hi:[0,1]
	v_pk_mul_f32 v[144:145], v[140:141], v[144:145] op_sel_hi:[0,1]
	v_pk_mul_f32 v[160:161], v[140:141], v[160:161] op_sel_hi:[0,1]
	v_pk_mul_f32 v[162:163], v[140:141], v[162:163] op_sel_hi:[0,1]
	v_cvt_pk_bf16_f32 v144, v144, v145
	v_cvt_pk_bf16_f32 v145, v146, v147
	v_cvt_pk_bf16_f32 v146, v162, v163
	v_cvt_pk_bf16_f32 v147, v160, v161
	v_or_b32_e32 v160, 16, v150
	v_ashrrev_i32_e32 v161, 31, v160
	global_store_dwordx4 v[148:149], v[144:147], off offset:256
	s_nop 1
	v_lshl_add_u64 v[144:145], v[160:161], 2, s[12:13]
	s_nop 1
	v_mov_b32_e32 v162, v235
	v_mad_i64_i32 v[160:161], s[26:27], v160, s97, v[152:153]
	v_lshl_add_u64 v[160:161], v[160:161], 0, v[154:155]
	v_pk_mul_f32 v[146:147], v[118:119], v[162:163] op_sel_hi:[1,0]
	v_pk_mul_f32 v[148:149], v[120:121], v[162:163] op_sel_hi:[1,0]
	v_pk_mul_f32 v[164:165], v[114:115], v[162:163] op_sel_hi:[1,0]
	v_pk_mul_f32 v[166:167], v[116:117], v[162:163] op_sel_hi:[1,0]
	v_pk_mul_f32 v[148:149], v[140:141], v[148:149] op_sel_hi:[0,1]
	v_pk_mul_f32 v[146:147], v[140:141], v[146:147] op_sel_hi:[0,1]
	v_pk_mul_f32 v[166:167], v[140:141], v[166:167] op_sel_hi:[0,1]
	v_pk_mul_f32 v[164:165], v[140:141], v[164:165] op_sel_hi:[0,1]
	v_cvt_pk_bf16_f32 v146, v146, v147
	v_cvt_pk_bf16_f32 v147, v148, v149
	v_cvt_pk_bf16_f32 v148, v164, v165
	v_cvt_pk_bf16_f32 v149, v166, v167
	global_store_dwordx4 v[160:161], v[146:149], off
	v_pk_mul_f32 v[164:165], v[74:75], v[162:163] op_sel_hi:[1,0]
	s_nop 0
	v_pk_mul_f32 v[146:147], v[78:79], v[162:163] op_sel_hi:[1,0]
	v_pk_mul_f32 v[148:149], v[80:81], v[162:163] op_sel_hi:[1,0]
	v_pk_mul_f32 v[146:147], v[140:141], v[146:147] op_sel_hi:[0,1]
	v_pk_mul_f32 v[148:149], v[140:141], v[148:149] op_sel_hi:[0,1]
	v_pk_mul_f32 v[162:163], v[76:77], v[162:163] op_sel_hi:[1,0]
	v_pk_mul_f32 v[164:165], v[140:141], v[164:165] op_sel_hi:[0,1]
	v_cvt_pk_bf16_f32 v146, v146, v147
	v_cvt_pk_bf16_f32 v147, v148, v149
	v_cvt_pk_bf16_f32 v148, v164, v165
	v_pk_mul_f32 v[162:163], v[140:141], v[162:163] op_sel_hi:[0,1]
	v_cvt_pk_bf16_f32 v149, v162, v163
	global_store_dwordx4 v[160:161], v[146:149], off offset:256
	s_nop 1
	v_or_b32_e32 v148, 32, v150
	v_ashrrev_i32_e32 v149, 31, v148
	v_lshl_add_u64 v[146:147], v[148:149], 2, s[12:13]
	s_nop 1
	v_mov_b32_e32 v164, v236
	v_mad_i64_i32 v[148:149], s[26:27], v148, s97, v[152:153]
	v_lshl_add_u64 v[148:149], v[148:149], 0, v[154:155]
	v_pk_mul_f32 v[160:161], v[110:111], v[164:165] op_sel_hi:[1,0]
	v_pk_mul_f32 v[162:163], v[112:113], v[164:165] op_sel_hi:[1,0]
	v_pk_mul_f32 v[166:167], v[106:107], v[164:165] op_sel_hi:[1,0]
	v_pk_mul_f32 v[168:169], v[108:109], v[164:165] op_sel_hi:[1,0]
	v_pk_mul_f32 v[162:163], v[140:141], v[162:163] op_sel_hi:[0,1]
	v_pk_mul_f32 v[160:161], v[140:141], v[160:161] op_sel_hi:[0,1]
	v_pk_mul_f32 v[168:169], v[140:141], v[168:169] op_sel_hi:[0,1]
	v_pk_mul_f32 v[166:167], v[140:141], v[166:167] op_sel_hi:[0,1]
	v_cvt_pk_bf16_f32 v160, v160, v161
	v_cvt_pk_bf16_f32 v161, v162, v163
	v_cvt_pk_bf16_f32 v162, v166, v167
	v_cvt_pk_bf16_f32 v163, v168, v169
	global_store_dwordx4 v[148:149], v[160:163], off
	v_pk_mul_f32 v[166:167], v[86:87], v[164:165] op_sel_hi:[1,0]
	s_nop 0
	v_pk_mul_f32 v[160:161], v[94:95], v[164:165] op_sel_hi:[1,0]
	v_pk_mul_f32 v[162:163], v[96:97], v[164:165] op_sel_hi:[1,0]
	v_pk_mul_f32 v[164:165], v[88:89], v[164:165] op_sel_hi:[1,0]
	v_pk_mul_f32 v[162:163], v[140:141], v[162:163] op_sel_hi:[0,1]
; __device__ __forceinline__ unsigned cvt_pk_bf16(float lo, float hi) { unsigned r; asm volatile("v_cvt_pk_bf16_f32 %0, %1, %2" : "=v"(r) : "v"(lo), "v"(hi)); return r; }
; __device__ __forceinline__ float bf_lo(unsigned w) { return __uint_as_float(w << 16); }
; __device__ __forceinline__ float bf_hi(unsigned w) { return __uint_as_float(w & 0xffff0000u); }
; __device__ __forceinline__ float sigmoid_f(float x) { return __builtin_amdgcn_rcpf(1.0f + __builtin_amdgcn_exp2f(-1.4426950408889634f * x)); }
; #define RS ((float*)(WSP() + WS_RS))
;     __device__ __forceinline__ void operator()(const f32x4 (&acc)[2][2][4][2], const Unit& u, int wr, int wc, int fr, int fq) const {
;     ...
;             for (int m = 0; m < 4; ++m) { const size_t off = (size_t)(row0 + ai * HALF + m * 16) * ldc + col0; const float rs = (MODE != 0) ? RS[row0 + ai * HALF + m * 16] : 1.f;
; #pragma unroll
;                 for (int bj = 0; bj < 2; ++bj) { f32x4 v0 = acc[ai][bj][m][0], v1 = acc[ai][bj][m][1];
;                     if (MODE != 0) { v0 = v0 * rs; v1 = v1 * rs; }
;                     if (MODE == 1) {
; #pragma unroll
;                         for (int e = 0; e < 4; ++e) { const float a = fmaxf(v0[e], 0.f), b = fmaxf(v1[e], 0.f); v0[e] = a * a; v1[e] = b * b; } }
;                     if (MODE == 2) { v0 = v0 * sc; v1 = v1 * sc; }
;                     if (MODE == 3) { const u32x4 pw = *(const u32x4*)(P + off + bj * HALF);
;                         v0[0] = bf_lo(pw.x) * sigmoid_f(v0[0]); v0[1] = bf_hi(pw.x) * sigmoid_f(v0[1]); v0[2] = bf_lo(pw.y) * sigmoid_f(v0[2]); v0[3] = bf_hi(pw.y) * sigmoid_f(v0[3]);
;                         v1[0] = bf_lo(pw.z) * sigmoid_f(v1[0]); v1[1] = bf_hi(pw.z) * sigmoid_f(v1[1]); v1[2] = bf_lo(pw.w) * sigmoid_f(v1[2]); v1[3] = bf_hi(pw.w) * sigmoid_f(v1[3]); }
;                     u32x4 w; w.x = cvt_pk_bf16(v0[0], v0[1]); w.y = cvt_pk_bf16(v0[2], v0[3]); w.z = cvt_pk_bf16(v1[0], v1[1]); w.w = cvt_pk_bf16(v1[2], v1[3]);
;                     *(u32x4*)(O + off + bj * HALF) = w; } }
	v_pk_mul_f32 v[160:161], v[140:141], v[160:161] op_sel_hi:[0,1]
	v_pk_mul_f32 v[164:165], v[140:141], v[164:165] op_sel_hi:[0,1]
	v_pk_mul_f32 v[166:167], v[140:141], v[166:167] op_sel_hi:[0,1]
	v_cvt_pk_bf16_f32 v160, v160, v161
	v_cvt_pk_bf16_f32 v161, v162, v163
	v_cvt_pk_bf16_f32 v162, v166, v167
	v_cvt_pk_bf16_f32 v163, v164, v165
	v_or_b32_e32 v164, 48, v150
	v_ashrrev_i32_e32 v165, 31, v164
	global_store_dwordx4 v[148:149], v[160:163], off offset:256
	v_lshl_add_u64 v[148:149], v[164:165], 2, s[12:13]
	s_nop 1
	v_mov_b32_e32 v166, v237
	v_mad_i64_i32 v[164:165], s[26:27], v164, s97, v[152:153]
	v_lshl_add_u64 v[164:165], v[164:165], 0, v[154:155]
	v_pk_mul_f32 v[160:161], v[102:103], v[166:167] op_sel_hi:[1,0]
	v_pk_mul_f32 v[162:163], v[104:105], v[166:167] op_sel_hi:[1,0]
	v_pk_mul_f32 v[168:169], v[98:99], v[166:167] op_sel_hi:[1,0]
	v_pk_mul_f32 v[170:171], v[100:101], v[166:167] op_sel_hi:[1,0]
	v_pk_mul_f32 v[162:163], v[140:141], v[162:163] op_sel_hi:[0,1]
	v_pk_mul_f32 v[160:161], v[140:141], v[160:161] op_sel_hi:[0,1]
	v_pk_mul_f32 v[170:171], v[140:141], v[170:171] op_sel_hi:[0,1]
	v_pk_mul_f32 v[168:169], v[140:141], v[168:169] op_sel_hi:[0,1]
	v_cvt_pk_bf16_f32 v160, v160, v161
	v_cvt_pk_bf16_f32 v161, v162, v163
	v_cvt_pk_bf16_f32 v162, v168, v169
	v_cvt_pk_bf16_f32 v163, v170, v171
	global_store_dwordx4 v[164:165], v[160:163], off
	v_pk_mul_f32 v[168:169], v[66:67], v[166:167] op_sel_hi:[1,0]
	s_nop 0
	v_pk_mul_f32 v[160:161], v[70:71], v[166:167] op_sel_hi:[1,0]
	v_pk_mul_f32 v[162:163], v[72:73], v[166:167] op_sel_hi:[1,0]
	v_pk_mul_f32 v[166:167], v[68:69], v[166:167] op_sel_hi:[1,0]
	v_pk_mul_f32 v[162:163], v[140:141], v[162:163] op_sel_hi:[0,1]
	v_pk_mul_f32 v[160:161], v[140:141], v[160:161] op_sel_hi:[0,1]
	v_pk_mul_f32 v[166:167], v[140:141], v[166:167] op_sel_hi:[0,1]
	v_pk_mul_f32 v[168:169], v[140:141], v[168:169] op_sel_hi:[0,1]
	v_cvt_pk_bf16_f32 v160, v160, v161
	v_cvt_pk_bf16_f32 v161, v162, v163
	v_cvt_pk_bf16_f32 v162, v168, v169
	v_cvt_pk_bf16_f32 v163, v166, v167
	global_store_dwordx4 v[164:165], v[160:163], off offset:256
	s_nop 1
	v_mov_b32_e32 v164, v238
	v_pk_mul_f32 v[166:167], v[58:59], v[164:165] op_sel_hi:[1,0]
	v_pk_mul_f32 v[160:161], v[62:63], v[164:165] op_sel_hi:[1,0]
	v_pk_mul_f32 v[162:163], v[64:65], v[164:165] op_sel_hi:[1,0]
	v_pk_mul_f32 v[160:161], v[140:141], v[160:161] op_sel_hi:[0,1]
	v_pk_mul_f32 v[162:163], v[140:141], v[162:163] op_sel_hi:[0,1]
	v_pk_mul_f32 v[166:167], v[140:141], v[166:167] op_sel_hi:[0,1]
	v_pk_mul_f32 v[168:169], v[60:61], v[164:165] op_sel_hi:[1,0]
	v_cvt_pk_bf16_f32 v160, v160, v161
	v_cvt_pk_bf16_f32 v161, v162, v163
	v_cvt_pk_bf16_f32 v162, v166, v167
	v_mad_i64_i32 v[166:167], s[26:27], v151, s97, v[152:153]
	v_pk_mul_f32 v[168:169], v[140:141], v[168:169] op_sel_hi:[0,1]
	v_cvt_pk_bf16_f32 v163, v168, v169
	v_lshl_add_u64 v[166:167], v[166:167], 0, v[154:155]
	global_store_dwordx4 v[166:167], v[160:163], off
	v_pk_mul_f32 v[168:169], v[18:19], v[164:165] op_sel_hi:[1,0]
	v_add_u32_e32 v151, 0x90, v150
	v_pk_mul_f32 v[160:161], v[26:27], v[164:165] op_sel_hi:[1,0]
	v_pk_mul_f32 v[162:163], v[28:29], v[164:165] op_sel_hi:[1,0]
	v_pk_mul_f32 v[164:165], v[20:21], v[164:165] op_sel_hi:[1,0]
	v_pk_mul_f32 v[162:163], v[140:141], v[162:163] op_sel_hi:[0,1]
	v_pk_mul_f32 v[160:161], v[140:141], v[160:161] op_sel_hi:[0,1]
	v_pk_mul_f32 v[164:165], v[140:141], v[164:165] op_sel_hi:[0,1]
	v_pk_mul_f32 v[168:169], v[140:141], v[168:169] op_sel_hi:[0,1]
	v_cvt_pk_bf16_f32 v160, v160, v161
	v_cvt_pk_bf16_f32 v161, v162, v163
	v_cvt_pk_bf16_f32 v162, v168, v169
	v_cvt_pk_bf16_f32 v163, v164, v165
	global_store_dwordx4 v[166:167], v[160:163], off offset:256
	s_nop 1
	v_mov_b32_e32 v164, v239
	v_pk_mul_f32 v[166:167], v[50:51], v[164:165] op_sel_hi:[1,0]
	v_pk_mul_f32 v[160:161], v[54:55], v[164:165] op_sel_hi:[1,0]
	v_pk_mul_f32 v[162:163], v[56:57], v[164:165] op_sel_hi:[1,0]
	v_pk_mul_f32 v[160:161], v[140:141], v[160:161] op_sel_hi:[0,1]
	v_pk_mul_f32 v[162:163], v[140:141], v[162:163] op_sel_hi:[0,1]
	v_pk_mul_f32 v[166:167], v[140:141], v[166:167] op_sel_hi:[0,1]
	v_pk_mul_f32 v[168:169], v[52:53], v[164:165] op_sel_hi:[1,0]
	v_cvt_pk_bf16_f32 v160, v160, v161
	v_cvt_pk_bf16_f32 v161, v162, v163
	v_cvt_pk_bf16_f32 v162, v166, v167
	v_mad_i64_i32 v[166:167], s[26:27], v151, s97, v[152:153]
	v_pk_mul_f32 v[168:169], v[140:141], v[168:169] op_sel_hi:[0,1]
	v_cvt_pk_bf16_f32 v163, v168, v169
	v_lshl_add_u64 v[166:167], v[166:167], 0, v[154:155]
	global_store_dwordx4 v[166:167], v[160:163], off
	v_pk_mul_f32 v[168:169], v[10:11], v[164:165] op_sel_hi:[1,0]
	v_add_u32_e32 v151, 0xa0, v150
	v_pk_mul_f32 v[160:161], v[14:15], v[164:165] op_sel_hi:[1,0]
	v_pk_mul_f32 v[162:163], v[16:17], v[164:165] op_sel_hi:[1,0]
	v_pk_mul_f32 v[164:165], v[12:13], v[164:165] op_sel_hi:[1,0]
	v_pk_mul_f32 v[162:163], v[140:141], v[162:163] op_sel_hi:[0,1]
	v_pk_mul_f32 v[160:161], v[140:141], v[160:161] op_sel_hi:[0,1]
	v_pk_mul_f32 v[164:165], v[140:141], v[164:165] op_sel_hi:[0,1]
	v_pk_mul_f32 v[168:169], v[140:141], v[168:169] op_sel_hi:[0,1]
	v_cvt_pk_bf16_f32 v160, v160, v161
	v_cvt_pk_bf16_f32 v161, v162, v163
	v_cvt_pk_bf16_f32 v162, v168, v169
	v_cvt_pk_bf16_f32 v163, v164, v165
	global_store_dwordx4 v[166:167], v[160:163], off offset:256
	s_nop 1
	v_mov_b32_e32 v164, v240
	v_pk_mul_f32 v[166:167], v[42:43], v[164:165] op_sel_hi:[1,0]
	v_pk_mul_f32 v[160:161], v[46:47], v[164:165] op_sel_hi:[1,0]
	v_pk_mul_f32 v[162:163], v[48:49], v[164:165] op_sel_hi:[1,0]
	v_pk_mul_f32 v[160:161], v[140:141], v[160:161] op_sel_hi:[0,1]
	v_pk_mul_f32 v[162:163], v[140:141], v[162:163] op_sel_hi:[0,1]
; __device__ __forceinline__ unsigned cvt_pk_bf16(float lo, float hi) { unsigned r; asm volatile("v_cvt_pk_bf16_f32 %0, %1, %2" : "=v"(r) : "v"(lo), "v"(hi)); return r; }
; __device__ __forceinline__ float bf_lo(unsigned w) { return __uint_as_float(w << 16); }
; __device__ __forceinline__ float bf_hi(unsigned w) { return __uint_as_float(w & 0xffff0000u); }
; __device__ __forceinline__ float sigmoid_f(float x) { return __builtin_amdgcn_rcpf(1.0f + __builtin_amdgcn_exp2f(-1.4426950408889634f * x)); }
; #define RS ((float*)(WSP() + WS_RS))
;     __device__ __forceinline__ void operator()(const f32x4 (&acc)[2][2][4][2], const Unit& u, int wr, int wc, int fr, int fq) const {
;     ...
;             for (int m = 0; m < 4; ++m) { const size_t off = (size_t)(row0 + ai * HALF + m * 16) * ldc + col0; const float rs = (MODE != 0) ? RS[row0 + ai * HALF + m * 16] : 1.f;
; #pragma unroll
;                 for (int bj = 0; bj < 2; ++bj) { f32x4 v0 = acc[ai][bj][m][0], v1 = acc[ai][bj][m][1];
;                     if (MODE != 0) { v0 = v0 * rs; v1 = v1 * rs; }
;                     if (MODE == 1) {
; #pragma unroll
;                         for (int e = 0; e < 4; ++e) { const float a = fmaxf(v0[e], 0.f), b = fmaxf(v1[e], 0.f); v0[e] = a * a; v1[e] = b * b; } }
;                     if (MODE == 2) { v0 = v0 * sc; v1 = v1 * sc; }
;                     if (MODE == 3) { const u32x4 pw = *(const u32x4*)(P + off + bj * HALF);
;                         v0[0] = bf_lo(pw.x) * sigmoid_f(v0[0]); v0[1] = bf_hi(pw.x) * sigmoid_f(v0[1]); v0[2] = bf_lo(pw.y) * sigmoid_f(v0[2]); v0[3] = bf_hi(pw.y) * sigmoid_f(v0[3]);
;                         v1[0] = bf_lo(pw.z) * sigmoid_f(v1[0]); v1[1] = bf_hi(pw.z) * sigmoid_f(v1[1]); v1[2] = bf_lo(pw.w) * sigmoid_f(v1[2]); v1[3] = bf_hi(pw.w) * sigmoid_f(v1[3]); }
;                     u32x4 w; w.x = cvt_pk_bf16(v0[0], v0[1]); w.y = cvt_pk_bf16(v0[2], v0[3]); w.z = cvt_pk_bf16(v1[0], v1[1]); w.w = cvt_pk_bf16(v1[2], v1[3]);
;                     *(u32x4*)(O + off + bj * HALF) = w; } }
	v_pk_mul_f32 v[166:167], v[140:141], v[166:167] op_sel_hi:[0,1]
	v_pk_mul_f32 v[168:169], v[44:45], v[164:165] op_sel_hi:[1,0]
	v_cvt_pk_bf16_f32 v160, v160, v161
	v_cvt_pk_bf16_f32 v161, v162, v163
	v_cvt_pk_bf16_f32 v162, v166, v167
	v_mad_i64_i32 v[166:167], s[26:27], v151, s97, v[152:153]
	v_pk_mul_f32 v[168:169], v[140:141], v[168:169] op_sel_hi:[0,1]
	v_cvt_pk_bf16_f32 v163, v168, v169
	v_lshl_add_u64 v[166:167], v[166:167], 0, v[154:155]
	global_store_dwordx4 v[166:167], v[160:163], off
	v_pk_mul_f32 v[168:169], v[22:23], v[164:165] op_sel_hi:[1,0]
	v_add_u32_e32 v151, 0xb0, v150
	v_pk_mul_f32 v[160:161], v[30:31], v[164:165] op_sel_hi:[1,0]
	v_pk_mul_f32 v[162:163], v[32:33], v[164:165] op_sel_hi:[1,0]
	v_pk_mul_f32 v[164:165], v[24:25], v[164:165] op_sel_hi:[1,0]
	v_pk_mul_f32 v[162:163], v[140:141], v[162:163] op_sel_hi:[0,1]
	v_pk_mul_f32 v[160:161], v[140:141], v[160:161] op_sel_hi:[0,1]
	v_pk_mul_f32 v[164:165], v[140:141], v[164:165] op_sel_hi:[0,1]
	v_pk_mul_f32 v[168:169], v[140:141], v[168:169] op_sel_hi:[0,1]
	v_cvt_pk_bf16_f32 v160, v160, v161
	v_cvt_pk_bf16_f32 v161, v162, v163
	v_cvt_pk_bf16_f32 v162, v168, v169
	v_cvt_pk_bf16_f32 v163, v164, v165
	global_store_dwordx4 v[166:167], v[160:163], off offset:256
	s_nop 1
	v_mov_b32_e32 v150, v241
	v_mad_i64_i32 v[152:153], s[26:27], v151, s97, v[152:153]
	v_lshl_add_u64 v[154:155], v[152:153], 0, v[154:155]
	v_pk_mul_f32 v[160:161], v[38:39], v[150:151] op_sel_hi:[1,0]
	v_pk_mul_f32 v[162:163], v[40:41], v[150:151] op_sel_hi:[1,0]
	v_pk_mul_f32 v[164:165], v[34:35], v[150:151] op_sel_hi:[1,0]
	v_pk_mul_f32 v[166:167], v[36:37], v[150:151] op_sel_hi:[1,0]
	v_pk_mul_f32 v[162:163], v[140:141], v[162:163] op_sel_hi:[0,1]
	v_pk_mul_f32 v[160:161], v[140:141], v[160:161] op_sel_hi:[0,1]
	v_pk_mul_f32 v[166:167], v[140:141], v[166:167] op_sel_hi:[0,1]
	v_pk_mul_f32 v[164:165], v[140:141], v[164:165] op_sel_hi:[0,1]
	v_cvt_pk_bf16_f32 v160, v160, v161
	v_cvt_pk_bf16_f32 v161, v162, v163
	v_cvt_pk_bf16_f32 v162, v164, v165
	v_cvt_pk_bf16_f32 v163, v166, v167
	v_pk_mul_f32 v[152:153], v[6:7], v[150:151] op_sel_hi:[1,0]
	global_store_dwordx4 v[154:155], v[160:163], off
	v_pk_mul_f32 v[152:153], v[140:141], v[152:153] op_sel_hi:[0,1]
	s_nop 0
	v_pk_mul_f32 v[160:161], v[8:9], v[150:151] op_sel_hi:[1,0]
	v_pk_mul_f32 v[162:163], v[2:3], v[150:151] op_sel_hi:[1,0]
	v_pk_mul_f32 v[150:151], v[4:5], v[150:151] op_sel_hi:[1,0]
	v_pk_mul_f32 v[160:161], v[140:141], v[160:161] op_sel_hi:[0,1]
	v_pk_mul_f32 v[164:165], v[140:141], v[150:151] op_sel_hi:[0,1]
	v_pk_mul_f32 v[162:163], v[140:141], v[162:163] op_sel_hi:[0,1]
	v_cvt_pk_bf16_f32 v150, v152, v153
	v_cvt_pk_bf16_f32 v151, v160, v161
	v_cvt_pk_bf16_f32 v152, v162, v163
	v_cvt_pk_bf16_f32 v153, v164, v165
	global_store_dwordx4 v[154:155], v[150:153], off offset:256
	s_cbranch_scc1 .LBB0_199
; #define RS ((float*)(WSP() + WS_RS))
;     __device__ __forceinline__ void operator()(const f32x4 (&acc)[2][2][4][2], const Unit& u, int wr, int wc, int fr, int fq) const {
;     ...
;         if (MODE == 2) { if (u.pn == qtile || u.pn == qtile + 1) {
; #pragma unroll
;             for (int ai = 0; ai < 2; ++ai)
; #pragma unroll
;                 for (int bj = 0; bj < 2; ++bj) { float mx = 0.f;
; #pragma unroll
;                     for (int m = 0; m < 4; ++m) { const float rs = RS[row0 + ai * HALF + m * 16] * sc; const f32x4 v0 = acc[ai][bj][m][0] * rs, v1 = acc[ai][bj][m][1] * rs;
;                         float ss = ((v0[0] * v0[0] + v0[1] * v0[1]) + (v0[2] * v0[2] + v0[3] * v0[3])) + ((v1[0] * v1[0] + v1[1] * v1[1]) + (v1[2] * v1[2] + v1[3] * v1[3]));
;                         ss += __shfl_xor(ss, 16); ss += __shfl_xor(ss, 32); mx = fmaxf(mx, ss); }
;                     mx = fmaxf(mx, __shfl_xor(mx, 1)); mx = fmaxf(mx, __shfl_xor(mx, 2)); mx = fmaxf(mx, __shfl_xor(mx, 4)); mx = fmaxf(mx, __shfl_xor(mx, 8));
	s_nop 1
	v_mov_b32_e32 v160, v234
	v_cmp_lt_i32_e32 vcc, v208, v203
	s_lshl_b32 s19, s25, 12
	s_lshl_b32 s17, s24, 4
	v_cndmask_b32_e32 v150, v201, v208, vcc
	v_lshlrev_b32_e32 v155, 2, v150
	v_cmp_lt_i32_e32 vcc, v209, v203
	s_add_i32 s19, s81, s19
	s_add_i32 s17, s19, s17
	v_cndmask_b32_e32 v150, v201, v209, vcc
	v_lshlrev_b32_e32 v154, 2, v150
	v_cmp_lt_i32_e32 vcc, v204, v203
	s_or_b32 s24, s17, s78
	v_mul_f32_e32 v160, v140, v160
	v_pk_mul_f32 v[126:127], v[126:127], v[160:161] op_sel_hi:[1,0]
	v_pk_mul_f32 v[122:123], v[122:123], v[160:161] op_sel_hi:[1,0]
	v_pk_mul_f32 v[128:129], v[128:129], v[160:161] op_sel_hi:[1,0]
	v_pk_mul_f32 v[124:125], v[124:125], v[160:161] op_sel_hi:[1,0]
	v_mul_f32_e32 v127, v127, v127
	v_mul_f32_e32 v123, v123, v123
	v_fmac_f32_e32 v127, v126, v126
	v_mul_f32_e32 v126, v129, v129
	v_fmac_f32_e32 v123, v122, v122
	v_mul_f32_e32 v122, v125, v125
	v_fmac_f32_e32 v126, v128, v128
	v_fmac_f32_e32 v122, v124, v124
	v_add_f32_e32 v126, v127, v126
	v_add_f32_e32 v122, v123, v122
	v_add_f32_e32 v122, v126, v122
	ds_bpermute_b32 v123, v155, v122
	v_cndmask_b32_e32 v150, v201, v204, vcc
	v_lshlrev_b32_e32 v150, 2, v150
	v_cmp_lt_i32_e32 vcc, v205, v203
	s_waitcnt lgkmcnt(0)
	v_add_f32_e32 v122, v122, v123
	ds_bpermute_b32 v123, v154, v122
	v_cndmask_b32_e32 v151, v201, v205, vcc
	v_lshlrev_b32_e32 v151, 2, v151
	v_cmp_lt_i32_e32 vcc, v206, v203
	s_waitcnt lgkmcnt(0)
	v_add_f32_e32 v123, v122, v123
	s_nop 1
	v_mov_b32_e32 v122, v235
	v_cndmask_b32_e32 v152, v201, v206, vcc
	v_lshlrev_b32_e32 v152, 2, v152
	v_cmp_lt_i32_e32 vcc, v207, v203
	v_mul_f32_e32 v122, v140, v122
	v_pk_mul_f32 v[118:119], v[118:119], v[122:123] op_sel_hi:[1,0]
	v_pk_mul_f32 v[114:115], v[114:115], v[122:123] op_sel_hi:[1,0]
	v_pk_mul_f32 v[120:121], v[120:121], v[122:123] op_sel_hi:[1,0]
	v_pk_mul_f32 v[116:117], v[116:117], v[122:123] op_sel_hi:[1,0]
	v_mul_f32_e32 v119, v119, v119
	v_mul_f32_e32 v115, v115, v115
	v_fmac_f32_e32 v119, v118, v118
	v_mul_f32_e32 v118, v121, v121
	v_fmac_f32_e32 v115, v114, v114
	v_mul_f32_e32 v114, v117, v117
	v_fmac_f32_e32 v118, v120, v120
	v_fmac_f32_e32 v114, v116, v116
	v_add_f32_e32 v118, v119, v118
	v_add_f32_e32 v114, v115, v114
	v_add_f32_e32 v114, v118, v114
	ds_bpermute_b32 v115, v155, v114
	v_cndmask_b32_e32 v153, v201, v207, vcc
	v_lshlrev_b32_e32 v153, 2, v153
	s_waitcnt lgkmcnt(0)
	v_add_f32_e32 v114, v114, v115
	ds_bpermute_b32 v115, v154, v114
	s_waitcnt lgkmcnt(0)
	v_add_f32_e32 v114, v114, v115
	v_max3_f32 v115, v123, 0, v114
	s_nop 1
	v_mov_b32_e32 v114, v236
	v_mul_f32_e32 v114, v140, v114
	v_pk_mul_f32 v[110:111], v[110:111], v[114:115] op_sel_hi:[1,0]
	v_pk_mul_f32 v[106:107], v[106:107], v[114:115] op_sel_hi:[1,0]
	v_pk_mul_f32 v[112:113], v[112:113], v[114:115] op_sel_hi:[1,0]
	v_pk_mul_f32 v[108:109], v[108:109], v[114:115] op_sel_hi:[1,0]
	v_mul_f32_e32 v111, v111, v111
	v_mul_f32_e32 v107, v107, v107
	v_fmac_f32_e32 v111, v110, v110
	v_mul_f32_e32 v110, v113, v113
	v_fmac_f32_e32 v107, v106, v106
	v_mul_f32_e32 v106, v109, v109
	v_fmac_f32_e32 v110, v112, v112
	v_fmac_f32_e32 v106, v108, v108
	v_add_f32_e32 v110, v111, v110
	v_add_f32_e32 v106, v107, v106
	v_add_f32_e32 v106, v110, v106
	ds_bpermute_b32 v107, v155, v106
	s_waitcnt lgkmcnt(0)
	v_add_f32_e32 v106, v106, v107
	ds_bpermute_b32 v107, v154, v106
	s_waitcnt lgkmcnt(0)
	v_add_f32_e32 v107, v106, v107
	s_nop 1
	v_mov_b32_e32 v106, v237
	v_mul_f32_e32 v106, v140, v106
	v_pk_mul_f32 v[102:103], v[102:103], v[106:107] op_sel_hi:[1,0]
	v_pk_mul_f32 v[98:99], v[98:99], v[106:107] op_sel_hi:[1,0]
	v_pk_mul_f32 v[104:105], v[104:105], v[106:107] op_sel_hi:[1,0]
	v_pk_mul_f32 v[100:101], v[100:101], v[106:107] op_sel_hi:[1,0]
	v_mul_f32_e32 v103, v103, v103
	v_mul_f32_e32 v99, v99, v99
	v_fmac_f32_e32 v103, v102, v102
	v_mul_f32_e32 v102, v105, v105
	v_fmac_f32_e32 v99, v98, v98
	v_mul_f32_e32 v98, v101, v101
	v_fmac_f32_e32 v102, v104, v104
	v_fmac_f32_e32 v98, v100, v100
	v_add_f32_e32 v102, v103, v102
	v_add_f32_e32 v98, v99, v98
	v_add_f32_e32 v98, v102, v98
	ds_bpermute_b32 v99, v155, v98
	s_waitcnt lgkmcnt(0)
	v_add_f32_e32 v98, v98, v99
	ds_bpermute_b32 v99, v154, v98
	s_waitcnt lgkmcnt(0)
	v_add_f32_e32 v98, v98, v99
	v_max3_f32 v98, v115, v107, v98
	ds_bpermute_b32 v99, v150, v98
	s_waitcnt lgkmcnt(0)
	v_max_f32_e32 v99, v99, v99
	v_max_f32_e32 v98, v98, v99
	ds_bpermute_b32 v99, v151, v98
	s_waitcnt lgkmcnt(0)
	v_max_f32_e32 v99, v99, v99
	v_max_f32_e32 v98, v98, v99
	ds_bpermute_b32 v99, v152, v98
	s_waitcnt lgkmcnt(0)
	v_max_f32_e32 v99, v99, v99
	v_max_f32_e32 v98, v98, v99
	ds_bpermute_b32 v99, v153, v98
	s_and_saveexec_b64 s[26:27], s[4:5]
	s_cbranch_execz .LBB0_192
	s_ashr_i32 s25, s24, 31
	s_lshl_b64 s[28:29], s[24:25], 2
	s_add_u32 s28, s73, s28
	s_waitcnt lgkmcnt(0)
	v_max_f32_e32 v99, v99, v99
	v_max_f32_e32 v98, v98, v98
	s_addc_u32 s29, s74, s29
	v_max_f32_e32 v98, v98, v99
	global_store_dword v1, v98, s[28:29]
	s_nop 1
	v_mov_b32_e32 v98, v236
	v_mul_f32_e32 v114, v140, v98
